# S5 MFMA waves: output store address kept as a running pointer (one 64-bit add per iteration instead of three VALU address ops)
# baseline (speedup 1.0000x reference)
; #define LAS __attribute__((address_space(3)))
; __device__ __forceinline__ void s5_phase(const Ctx& C, const bf16_t* U, bf16_t* Gout, const float* ABAR, const bf16_t* BB, const bf16_t* CM, const float* Dsk) {
;     ...
;             const bf16_t* up = U + tokb * DM + 16 * g + 8 * g4;
;             const LAS unsigned char* uring = C.lds + 100352 + pw * 4096;
;             const unsigned uoff = (unsigned)(2 * fr + g4) * 16u;
;     ...
;                     *(u32x2*)(Gout + (tokb + 16 * (i - 1) + fr) * DM + 16 * g + 4 * g4) = o;
.LBB0_203:
	s_or_b64 exec, exec, s[22:23]
	v_or_b32_e32 v64, v32, v63
	v_lshl_add_u64 v[44:45], v[64:65], 1, v[68:69]
	global_load_dwordx4 v[32:35], v[44:45], off
	global_load_dwordx4 v[36:39], v[44:45], off offset:64
	global_load_dwordx4 v[40:43], v[44:45], off offset:128
	s_nop 0
	global_load_dwordx4 v[44:47], v[44:45], off offset:192
	v_lshlrev_b32_e32 v48, 2, v60
	v_lshl_or_b32 v64, s38, 6, v48
	v_lshl_add_u64 v[48:49], s[60:61], 0, v[64:65]
	v_readlane_b32 s22, v255, 6
	flat_load_dword v48, v[48:49]
	s_waitcnt vmcnt(0) lgkmcnt(0)
	v_cvt_pk_bf16_f32 v51, v48, v65
	v_readlane_b32 s23, v255, 7
	v_and_b32_e32 v52, 0xffff, v51
	v_readlane_b32 s40, v255, 0
	v_cndmask_b32_e64 v48, 0, v52, s[22:23]
	s_mov_b32 s22, 0x5040100
	v_perm_b32 v49, v51, v48, s22
	v_readlane_b32 s41, v255, 1
	s_waitcnt lgkmcnt(0)
	s_barrier
	s_lshl_b32 s96, s38, 5
	v_cndmask_b32_e64 v48, v48, v49, s[40:41]
	v_readlane_b32 s40, v255, 2
	v_readlane_b32 s41, v255, 3
	v_mov_b32_e32 v77, s73
	v_or_b32_e32 v76, s72, v60
	v_cndmask_b32_e64 v49, 0, v52, s[40:41]
	v_readlane_b32 s40, v255, 20
	v_perm_b32 v50, v51, v49, s22
	v_readlane_b32 s41, v255, 21
	v_lshl_add_u64 v[78:79], v[70:71], 0, s[96:97]
	v_lshlrev_b64 v[130:131], 12, v[76:77]
	v_lshl_add_u64 v[130:131], v[78:79], 0, v[130:131]
	v_mov_b32_e32 v132, 0x10000
	v_mov_b32_e32 v133, 0
	s_movk_i32 s38, 0xc00
	v_cndmask_b32_e64 v49, v49, v50, s[40:41]
	v_readlane_b32 s40, v255, 22
	v_readlane_b32 s41, v255, 23
	s_mov_b32 s72, -2
	s_movk_i32 s96, 0xffe0
	v_cndmask_b32_e64 v50, 0, v52, s[40:41]
	v_cndmask_b32_e64 v52, 0, v52, s[56:57]
	v_perm_b32 v53, v51, v50, s22
	v_perm_b32 v51, v51, v52, s22
	v_cndmask_b32_e64 v50, v50, v53, s[54:55]
	v_cndmask_b32_e64 v51, v52, v51, s[58:59]
	v_mov_b32_e32 v52, 0
	v_mov_b32_e32 v56, 0
	v_mov_b32_e32 v57, 0
	v_mov_b32_e32 v58, 0
	v_mov_b32_e32 v59, 0
	s_and_saveexec_b64 s[80:81], s[42:43]
	s_add_i32 s40, s38, 0xfffff400
	s_and_b32 s40, s40, 0xe00
	v_add_u32_e32 v53, s40, v83
	ds_read_b128 v[56:59], v53
	s_or_b64 exec, exec, s[80:81]
	v_mov_b32_e32 v53, 0
	v_mov_b32_e32 v54, 0
	v_mov_b32_e32 v55, 0
	s_and_saveexec_b64 s[80:81], s[42:43]
	s_and_b32 s40, s38, 0xe00
	v_add_u32_e32 v52, s40, v83
	ds_read_b128 v[52:55], v52
	s_or_b64 exec, exec, s[80:81]
	s_branch .LBB0_205

; #define LAS __attribute__((address_space(3)))
; __device__ __forceinline__ unsigned cvt_pk_bf16_c(float lo, float hi) { f32x2 v = {lo, hi}; bf16x2_t b = __builtin_convertvector(v, bf16x2_t); return __builtin_bit_cast(unsigned, b); }
; __device__ __forceinline__ void s5_phase(const Ctx& C, const bf16_t* U, bf16_t* Gout, const float* ABAR, const bf16_t* BB, const bf16_t* CM, const float* Dsk) {
;     ...
;                 const bf16x8 uf = g4 < 2 ? *(const LAS bf16x8*)(uring + ((i + 1) & 7) * 512 + uoff) : zero8;
;                 const bf16x8 us = g4 < 2 ? *(const LAS bf16x8*)(uring + ((i - 1) & 7) * 512 + uoff) : zero8;
;                 const LAS unsigned char* src = hb + ((i - 1) & 1) * (S5_SUB * S5_HP) + fr * S5_HP + 16 * g4;
;                 bf16x8 hf[4];
; #pragma unroll
;                 for (int kk = 0; kk < 4; ++kk) hf[kk] = *(const LAS bf16x8*)(src + 64 * kk);
;                 LAS unsigned char* dst = bub + ((i + 1) & 1) * 4096;
;                 f32x4 a[8];
; #pragma unroll
;                 for (int n = 0; n < 8; ++n) a[n] = __builtin_amdgcn_mfma_f32_16x16x32_bf16(uf, bfr[n], (f32x4){0.f, 0.f, 0.f, 0.f}, 0, 0, 0);
;                 f32x4 y1 = __builtin_amdgcn_mfma_f32_16x16x32_bf16(dfr, us, (f32x4){0.f, 0.f, 0.f, 0.f}, 0, 0, 0);
;                 f32x4 y2 = __builtin_amdgcn_mfma_f32_16x16x32_bf16(cfr[2], hf[2], (f32x4){0.f, 0.f, 0.f, 0.f}, 0, 0, 0);
;                 y1 = __builtin_amdgcn_mfma_f32_16x16x32_bf16(cfr[0], hf[0], y1, 0, 0, 0);
;                 y2 = __builtin_amdgcn_mfma_f32_16x16x32_bf16(cfr[3], hf[3], y2, 0, 0, 0);
;                 y1 = __builtin_amdgcn_mfma_f32_16x16x32_bf16(cfr[1], hf[1], y1, 0, 0, 0);
; #pragma unroll
;                 for (int n = 0; n < 4; ++n) { u32x4 w;
;                     w.x = cvt_pk_bf16_c(a[n][0], a[n + 4][0]); w.y = cvt_pk_bf16_c(a[n][1], a[n + 4][1]); w.z = cvt_pk_bf16_c(a[n][2], a[n + 4][2]); w.w = cvt_pk_bf16_c(a[n][3], a[n + 4][3]);
;                     *(LAS u32x4*)(dst + ((g4 * 64) + 16 * n + fr) * 16) = w; }
;                 const f32x4 y = y1 + y2;
;                 if (i >= 1) {
;                     u32x2 o; o.x = cvt_pk_bf16_c(gelu_f(y[0]), gelu_f(y[1])); o.y = cvt_pk_bf16_c(gelu_f(y[2]), gelu_f(y[3]));
;                     *(u32x2*)(Gout + (tokb + 16 * (i - 1) + fr) * DM + 16 * g + 4 * g4) = o;
;                 }
.LBB0_205:
	s_add_i32 s22, s72, 1
	s_waitcnt lgkmcnt(0)
	v_mfma_f32_16x16x32_bf16 v[86:89], v[56:59], v[4:7], 0
	s_bitcmp1_b32 s72, 0
	s_cselect_b32 s23, 0x1100, 0
	v_add_u32_e32 v64, s23, v84
	v_mfma_f32_16x16x32_bf16 v[110:113], v[56:59], v[16:19], 0
	ds_read_b128 v[102:105], v64
	ds_read_b128 v[106:109], v64 offset:64
	ds_read_b128 v[114:117], v64 offset:128
	ds_read_b128 v[118:121], v64 offset:192
	s_and_b32 s23, s39, 0x1000
	v_mfma_f32_16x16x32_bf16 v[90:93], v[56:59], v[0:3], 0
	s_nop 1
	v_cvt_pk_bf16_f32 v86, v86, v110
	v_cvt_pk_bf16_f32 v87, v87, v111
	v_cvt_pk_bf16_f32 v88, v88, v112
	v_mfma_f32_16x16x32_bf16 v[122:125], v[56:59], v[24:27], 0
	v_cvt_pk_bf16_f32 v89, v89, v113
	v_add_u32_e32 v64, s23, v85
	ds_write_b128 v64, v[86:89]
	v_mfma_f32_16x16x32_bf16 v[94:97], v[56:59], v[12:15], 0
	s_cmp_lt_i32 s22, 1
	s_nop 2
	v_cvt_pk_bf16_f32 v86, v90, v122
	v_cvt_pk_bf16_f32 v87, v91, v123
	v_mfma_f32_16x16x32_bf16 v[126:129], v[56:59], v[20:23], 0
	v_cvt_pk_bf16_f32 v88, v92, v124
	v_cvt_pk_bf16_f32 v89, v93, v125
	ds_write_b128 v64, v[86:89] offset:256
	v_mfma_f32_16x16x32_bf16 v[52:55], v[48:51], v[52:55], 0
	v_mfma_f32_16x16x32_bf16 v[98:101], v[56:59], v[8:11], 0
	s_nop 2
	v_cvt_pk_bf16_f32 v86, v94, v126
	v_cvt_pk_bf16_f32 v87, v95, v127
	v_cvt_pk_bf16_f32 v88, v96, v128
	v_mfma_f32_16x16x32_bf16 v[56:59], v[56:59], v[28:31], 0
	v_cvt_pk_bf16_f32 v89, v97, v129
	ds_write_b128 v64, v[86:89] offset:512
	s_waitcnt lgkmcnt(4)
	v_mfma_f32_16x16x32_bf16 v[90:93], v[40:43], v[114:117], 0
	v_mfma_f32_16x16x32_bf16 v[86:89], v[32:35], v[102:105], v[52:55]
	s_nop 2
	v_cvt_pk_bf16_f32 v56, v98, v56
	v_cvt_pk_bf16_f32 v57, v99, v57
	v_cvt_pk_bf16_f32 v58, v100, v58
	v_cvt_pk_bf16_f32 v59, v101, v59
	s_waitcnt lgkmcnt(3)
	v_mfma_f32_16x16x32_bf16 v[52:55], v[44:47], v[118:121], v[90:93]
	ds_write_b128 v64, v[56:59] offset:768
	v_mfma_f32_16x16x32_bf16 v[56:59], v[36:39], v[106:109], v[86:89]
	s_cbranch_scc1 .Lmy_s5_early
	s_nop 6
	v_pk_add_f32 v[52:53], v[52:53], v[56:57]
	v_pk_add_f32 v[54:55], v[54:55], v[58:59]
	v_mul_f32_e32 v56, 0x3d372713, v52
	v_mul_f32_e32 v57, 0x3d372713, v53
	v_mul_f32_e32 v58, 0x3d372713, v54
	v_mul_f32_e32 v59, 0x3d372713, v55
	v_fma_f32 v56, v52, v56, 1.0
	v_fma_f32 v57, v53, v57, 1.0
	v_fma_f32 v58, v54, v58, 1.0
	v_fma_f32 v59, v55, v59, 1.0
	v_mul_f32_e32 v56, v52, v56
	v_mul_f32_e32 v57, v53, v57
	v_mul_f32_e32 v58, v54, v58
	v_mul_f32_e32 v59, v55, v59
	v_mul_f32_e32 v56, 0xc0135761, v56
	v_mul_f32_e32 v57, 0xc0135761, v57
	v_mul_f32_e32 v58, 0xc0135761, v58
	v_mul_f32_e32 v59, 0xc0135761, v59
	v_exp_f32_e32 v56, v56
	v_exp_f32_e32 v57, v57
	v_exp_f32_e32 v58, v58
	v_exp_f32_e32 v59, v59
	v_add_f32_e32 v56, 1.0, v56
	v_add_f32_e32 v57, 1.0, v57
	v_add_f32_e32 v58, 1.0, v58
	v_add_f32_e32 v59, 1.0, v59
	v_rcp_f32_e32 v56, v56
	v_rcp_f32_e32 v57, v57
	v_rcp_f32_e32 v58, v58
	v_rcp_f32_e32 v59, v59
	v_pk_mul_f32 v[52:53], v[52:53], v[56:57]
	s_nop 0
	v_cvt_pk_bf16_f32 v52, v52, v53
	v_pk_mul_f32 v[54:55], v[54:55], v[58:59]
	s_nop 0
	v_cvt_pk_bf16_f32 v53, v54, v55
	global_store_dwordx2 v[130:131], v[52:53], off
	v_lshl_add_u64 v[130:131], v[130:131], 0, v[132:133]
	s_branch .LBB0_204
